# grid barrier: agent-scope acquire (buffer_inv sc1, L1 drop) issued on entry to the wait instead of after the release in all 12 inlined copies; v16 otherwise
# baseline (speedup 1.0000x reference)
; __device__ __forceinline__ unsigned xb_ld(unsigned* p)              { return __hip_atomic_load(p, __ATOMIC_RELAXED, __HIP_MEMORY_SCOPE_AGENT); }
; __device__ __forceinline__ unsigned xb_add(unsigned* p, unsigned v) { return __hip_atomic_fetch_add(p, v, __ATOMIC_RELAXED, __HIP_MEMORY_SCOPE_AGENT); }
; #define XB_SPIN(cond, bar) do { unsigned _sp = 0; while (cond) { __builtin_amdgcn_s_sleep(1); \
;     if ((++_sp & 255u) == 0u) { if (xb_ld(&(bar)[XB_TMO])) break; if (_sp > XB_SPIN_CAP) { atomicAdd(&(bar)[XB_TMO], 1u); break; } } } } while (0)
; __device__ __forceinline__ void xcd_barrier(const XcdBarrier& b) {
;     ...
;         const unsigned old = xb_add(&bar[XB_XSUB(b.x)], 1u);
;         const unsigned gen = old / nloc;
;         if (old + 1u == (gen + 1u) * nloc) {
;             __builtin_amdgcn_fence(__ATOMIC_RELEASE, "agent");
;             asm volatile("s_waitcnt vmcnt(0)" ::: "memory");
;             const unsigned og = xb_add(&bar[XB_TOP], 1u);
;             const unsigned tg = og / nx;
;             if (og + 1u == (tg + 1u) * nx) xb_add(&bar[XB_TOPGEN], 1u);
;             else XB_SPIN(xb_ld(&bar[XB_TOPGEN]) == tg, bar);
;             __builtin_amdgcn_fence(__ATOMIC_ACQUIRE, "agent");
;             xb_add(&bar[XB_XGEN(b.x)], 1u);
;             asm volatile("s_waitcnt vmcnt(0)" ::: "memory");
;         } else {
;             XB_SPIN(xb_ld(&bar[XB_XGEN(b.x)]) == gen, bar);
.LBB0_363:
	v_readlane_b32 s4, v251, 9
	v_mov_b32_e32 v4, 0
	v_mov_b32_e32 v2, 1
	v_readlane_b32 s5, v251, 10
	v_sub_u32_e32 v6, 0, v3
	s_nop 3
	global_atomic_add v5, v4, v2, s[4:5] sc0
	v_cvt_f32_u32_e32 v2, v3
	v_rcp_iflag_f32_e32 v2, v2
	s_nop 0
	v_mul_f32_e32 v2, 0x4f7ffffe, v2
	v_cvt_u32_f32_e32 v2, v2
	v_mul_lo_u32 v6, v6, v2
	v_mul_hi_u32 v6, v2, v6
	v_add_u32_e32 v2, v2, v6
	s_waitcnt vmcnt(0)
	v_mul_hi_u32 v2, v5, v2
	v_mul_lo_u32 v6, v2, v3
	v_sub_u32_e32 v6, v5, v6
	v_add_u32_e32 v7, 1, v2
	v_cmp_ge_u32_e32 vcc, v6, v3
	v_add_u32_e32 v5, 1, v5
	s_nop 0
	v_cndmask_b32_e32 v2, v2, v7, vcc
	v_sub_u32_e32 v7, v6, v3
	v_cndmask_b32_e32 v6, v6, v7, vcc
	v_add_u32_e32 v7, 1, v2
	v_cmp_ge_u32_e32 vcc, v6, v3
	s_nop 1
	v_cndmask_b32_e32 v2, v2, v7, vcc
	v_mul_lo_u32 v6, v3, v2
	v_add_u32_e32 v3, v6, v3
	v_cmp_ne_u32_e32 vcc, v5, v3
	s_and_saveexec_b64 s[4:5], vcc
	s_xor_b64 s[4:5], exec, s[4:5]
	s_cbranch_execz .LBB0_377
	v_readlane_b32 s6, v251, 11
	v_readlane_b32 s7, v251, 12
	s_waitcnt lgkmcnt(0)
	s_nop 3
	buffer_inv sc1
	global_load_dword v1, v4, s[6:7] sc1
	s_waitcnt vmcnt(0)
	v_cmp_eq_u32_e32 vcc, v1, v2
	s_and_saveexec_b64 s[6:7], vcc
	s_cbranch_execz .LBB0_376
	s_mov_b32 s3, 1
	s_mov_b64 s[8:9], 0
	v_mov_b32_e32 v1, 0
	s_branch .LBB0_367

; __device__ __forceinline__ unsigned xb_ld(unsigned* p)              { return __hip_atomic_load(p, __ATOMIC_RELAXED, __HIP_MEMORY_SCOPE_AGENT); }
; __device__ __forceinline__ unsigned xb_add(unsigned* p, unsigned v) { return __hip_atomic_fetch_add(p, v, __ATOMIC_RELAXED, __HIP_MEMORY_SCOPE_AGENT); }
; #define XB_SPIN(cond, bar) do { unsigned _sp = 0; while (cond) { __builtin_amdgcn_s_sleep(1); \
;     if ((++_sp & 255u) == 0u) { if (xb_ld(&(bar)[XB_TMO])) break; if (_sp > XB_SPIN_CAP) { atomicAdd(&(bar)[XB_TMO], 1u); break; } } } } while (0)
; __device__ __forceinline__ void xcd_barrier(const XcdBarrier& b) {
;     ...
;         if (old + 1u == (gen + 1u) * nloc) {
;             __builtin_amdgcn_fence(__ATOMIC_RELEASE, "agent");
;             asm volatile("s_waitcnt vmcnt(0)" ::: "memory");
;             const unsigned og = xb_add(&bar[XB_TOP], 1u);
;             const unsigned tg = og / nx;
;             if (og + 1u == (tg + 1u) * nx) xb_add(&bar[XB_TOPGEN], 1u);
;             else XB_SPIN(xb_ld(&bar[XB_TOPGEN]) == tg, bar);
;             __builtin_amdgcn_fence(__ATOMIC_ACQUIRE, "agent");
;             xb_add(&bar[XB_XGEN(b.x)], 1u);
;             asm volatile("s_waitcnt vmcnt(0)" ::: "memory");
;         } else {
;             XB_SPIN(xb_ld(&bar[XB_XGEN(b.x)]) == gen, bar);
;             __builtin_amdgcn_fence(__ATOMIC_ACQUIRE, "agent");
.LBB0_376:
	s_or_b64 exec, exec, s[6:7]
	s_waitcnt vmcnt(0)
	s_waitcnt vmcnt(0)
.LBB0_377:
	s_andn2_saveexec_b64 s[4:5], s[4:5]
	s_cbranch_execz .LBB0_395
	s_mov_b64 s[4:5], exec
	buffer_inv sc1
	buffer_wbl2 sc1
	s_waitcnt lgkmcnt(0)
	s_waitcnt vmcnt(0)
	v_mbcnt_lo_u32_b32 v2, s4, 0
	v_mbcnt_hi_u32_b32 v2, s5, v2
	v_cmp_eq_u32_e32 vcc, 0, v2
	s_and_saveexec_b64 s[6:7], vcc
	s_cbranch_execz .LBB0_380
	s_bcnt1_i32_b64 s3, s[4:5]
	v_readlane_b32 s4, v251, 13
	v_mov_b32_e32 v3, 0
	v_mov_b32_e32 v4, s3
	v_readlane_b32 s5, v251, 14
	s_nop 4
	global_atomic_add v3, v3, v4, s[4:5] sc0

; __device__ __forceinline__ unsigned xb_add(unsigned* p, unsigned v) { return __hip_atomic_fetch_add(p, v, __ATOMIC_RELAXED, __HIP_MEMORY_SCOPE_AGENT); }
; __device__ __forceinline__ void xcd_barrier(const XcdBarrier& b) {
;     ...
;             __builtin_amdgcn_fence(__ATOMIC_ACQUIRE, "agent");
;             xb_add(&bar[XB_XGEN(b.x)], 1u);
;             asm volatile("s_waitcnt vmcnt(0)" ::: "memory");
.LBB0_394:
	s_or_b64 exec, exec, s[4:5]
	v_readlane_b32 s4, v251, 11
	v_mov_b32_e32 v1, 0
	v_mov_b32_e32 v2, 1
	v_readlane_b32 s5, v251, 12
	s_waitcnt vmcnt(0)
	s_nop 0
	s_nop 2
	global_atomic_add v1, v2, s[4:5]
	s_waitcnt vmcnt(0)

; __device__ __forceinline__ unsigned xb_ld(unsigned* p)              { return __hip_atomic_load(p, __ATOMIC_RELAXED, __HIP_MEMORY_SCOPE_AGENT); }
; __device__ __forceinline__ unsigned xb_add(unsigned* p, unsigned v) { return __hip_atomic_fetch_add(p, v, __ATOMIC_RELAXED, __HIP_MEMORY_SCOPE_AGENT); }
; #define XB_SPIN(cond, bar) do { unsigned _sp = 0; while (cond) { __builtin_amdgcn_s_sleep(1); \
;     if ((++_sp & 255u) == 0u) { if (xb_ld(&(bar)[XB_TMO])) break; if (_sp > XB_SPIN_CAP) { atomicAdd(&(bar)[XB_TMO], 1u); break; } } } } while (0)
; __device__ __forceinline__ void xcd_barrier(const XcdBarrier& b) {
;     ...
;         const unsigned old = xb_add(&bar[XB_XSUB(b.x)], 1u);
;         const unsigned gen = old / nloc;
;         if (old + 1u == (gen + 1u) * nloc) {
;             __builtin_amdgcn_fence(__ATOMIC_RELEASE, "agent");
;             asm volatile("s_waitcnt vmcnt(0)" ::: "memory");
;             const unsigned og = xb_add(&bar[XB_TOP], 1u);
;             const unsigned tg = og / nx;
;             if (og + 1u == (tg + 1u) * nx) xb_add(&bar[XB_TOPGEN], 1u);
;             else XB_SPIN(xb_ld(&bar[XB_TOPGEN]) == tg, bar);
;             __builtin_amdgcn_fence(__ATOMIC_ACQUIRE, "agent");
;             xb_add(&bar[XB_XGEN(b.x)], 1u);
;             asm volatile("s_waitcnt vmcnt(0)" ::: "memory");
;         } else {
;             XB_SPIN(xb_ld(&bar[XB_XGEN(b.x)]) == gen, bar);
.LBB0_984:
	v_readlane_b32 s6, v251, 9
	v_readlane_b32 s7, v251, 10
	v_cvt_f32_u32_e32 v1, v4
	v_sub_u32_e32 v6, 0, v4
	v_rcp_iflag_f32_e32 v1, v1
	s_nop 1
	global_atomic_add v5, v3, v211, s[6:7] sc0
	v_mul_f32_e32 v1, 0x4f7ffffe, v1
	v_cvt_u32_f32_e32 v1, v1
	v_mul_lo_u32 v6, v6, v1
	v_mul_hi_u32 v6, v1, v6
	v_add_u32_e32 v1, v1, v6
	s_waitcnt vmcnt(0)
	v_mul_hi_u32 v1, v5, v1
	v_mul_lo_u32 v6, v1, v4
	v_sub_u32_e32 v6, v5, v6
	v_add_u32_e32 v7, 1, v1
	v_cmp_ge_u32_e32 vcc, v6, v4
	v_add_u32_e32 v5, 1, v5
	s_nop 0
	v_cndmask_b32_e32 v1, v1, v7, vcc
	v_sub_u32_e32 v7, v6, v4
	v_cndmask_b32_e32 v6, v6, v7, vcc
	v_add_u32_e32 v7, 1, v1
	v_cmp_ge_u32_e32 vcc, v6, v4
	s_nop 1
	v_cndmask_b32_e32 v1, v1, v7, vcc
	v_mul_lo_u32 v6, v4, v1
	v_add_u32_e32 v4, v6, v4
	v_cmp_ne_u32_e32 vcc, v5, v4
	s_and_saveexec_b64 s[6:7], vcc
	s_xor_b64 s[6:7], exec, s[6:7]
	s_cbranch_execz .LBB0_998
	v_readlane_b32 s8, v251, 11
	v_readlane_b32 s9, v251, 12
	s_waitcnt lgkmcnt(0)
	s_nop 3
	buffer_inv sc1
	global_load_dword v2, v3, s[8:9] sc1
	s_waitcnt vmcnt(0)
	v_cmp_eq_u32_e32 vcc, v2, v1
	s_and_saveexec_b64 s[8:9], vcc
	s_cbranch_execz .LBB0_997
	s_mov_b32 s24, 1
	s_mov_b64 s[10:11], 0
	s_branch .LBB0_988

; __device__ __forceinline__ unsigned xb_ld(unsigned* p)              { return __hip_atomic_load(p, __ATOMIC_RELAXED, __HIP_MEMORY_SCOPE_AGENT); }
; __device__ __forceinline__ unsigned xb_add(unsigned* p, unsigned v) { return __hip_atomic_fetch_add(p, v, __ATOMIC_RELAXED, __HIP_MEMORY_SCOPE_AGENT); }
; #define XB_SPIN(cond, bar) do { unsigned _sp = 0; while (cond) { __builtin_amdgcn_s_sleep(1); \
;     if ((++_sp & 255u) == 0u) { if (xb_ld(&(bar)[XB_TMO])) break; if (_sp > XB_SPIN_CAP) { atomicAdd(&(bar)[XB_TMO], 1u); break; } } } } while (0)
; __device__ __forceinline__ void xcd_barrier(const XcdBarrier& b) {
;     ...
;         if (old + 1u == (gen + 1u) * nloc) {
;             __builtin_amdgcn_fence(__ATOMIC_RELEASE, "agent");
;             asm volatile("s_waitcnt vmcnt(0)" ::: "memory");
;             const unsigned og = xb_add(&bar[XB_TOP], 1u);
;             const unsigned tg = og / nx;
;             if (og + 1u == (tg + 1u) * nx) xb_add(&bar[XB_TOPGEN], 1u);
;             else XB_SPIN(xb_ld(&bar[XB_TOPGEN]) == tg, bar);
;             __builtin_amdgcn_fence(__ATOMIC_ACQUIRE, "agent");
;             xb_add(&bar[XB_XGEN(b.x)], 1u);
;             asm volatile("s_waitcnt vmcnt(0)" ::: "memory");
;         } else {
;             XB_SPIN(xb_ld(&bar[XB_XGEN(b.x)]) == gen, bar);
;             __builtin_amdgcn_fence(__ATOMIC_ACQUIRE, "agent");
.LBB0_997:
	s_or_b64 exec, exec, s[8:9]
	s_waitcnt vmcnt(0)
	s_waitcnt vmcnt(0)
.LBB0_998:
	s_andn2_saveexec_b64 s[6:7], s[6:7]
	s_cbranch_execz .LBB0_1016
	s_mov_b64 s[6:7], exec
	buffer_inv sc1
	buffer_wbl2 sc1
	s_waitcnt lgkmcnt(0)
	s_waitcnt vmcnt(0)
	v_mbcnt_lo_u32_b32 v1, s6, 0
	v_mbcnt_hi_u32_b32 v1, s7, v1
	v_cmp_eq_u32_e32 vcc, 0, v1
	s_and_saveexec_b64 s[8:9], vcc
	s_cbranch_execz .LBB0_1001
	s_bcnt1_i32_b64 s6, s[6:7]
	v_mov_b32_e32 v4, s6
	v_readlane_b32 s6, v251, 13
	v_readlane_b32 s7, v251, 14
	s_nop 4
	global_atomic_add v4, v3, v4, s[6:7] sc0

; __device__ __forceinline__ unsigned xb_add(unsigned* p, unsigned v) { return __hip_atomic_fetch_add(p, v, __ATOMIC_RELAXED, __HIP_MEMORY_SCOPE_AGENT); }
; __device__ __forceinline__ void xcd_barrier(const XcdBarrier& b) {
;     ...
;             __builtin_amdgcn_fence(__ATOMIC_ACQUIRE, "agent");
;             xb_add(&bar[XB_XGEN(b.x)], 1u);
;             asm volatile("s_waitcnt vmcnt(0)" ::: "memory");
.LBB0_1015:
	s_or_b64 exec, exec, s[6:7]
	v_readlane_b32 s6, v251, 11
	v_readlane_b32 s7, v251, 12
	s_waitcnt vmcnt(0)
	s_nop 0
	s_nop 2
	global_atomic_add v3, v211, s[6:7]
	s_waitcnt vmcnt(0)

; __device__ __forceinline__ unsigned xb_ld(unsigned* p)              { return __hip_atomic_load(p, __ATOMIC_RELAXED, __HIP_MEMORY_SCOPE_AGENT); }
; __device__ __forceinline__ unsigned xb_add(unsigned* p, unsigned v) { return __hip_atomic_fetch_add(p, v, __ATOMIC_RELAXED, __HIP_MEMORY_SCOPE_AGENT); }
; #define XB_SPIN(cond, bar) do { unsigned _sp = 0; while (cond) { __builtin_amdgcn_s_sleep(1); \
;     if ((++_sp & 255u) == 0u) { if (xb_ld(&(bar)[XB_TMO])) break; if (_sp > XB_SPIN_CAP) { atomicAdd(&(bar)[XB_TMO], 1u); break; } } } } while (0)
; __device__ __forceinline__ void xcd_barrier(const XcdBarrier& b) {
;     ...
;         const unsigned old = xb_add(&bar[XB_XSUB(b.x)], 1u);
;         const unsigned gen = old / nloc;
;         if (old + 1u == (gen + 1u) * nloc) {
;             __builtin_amdgcn_fence(__ATOMIC_RELEASE, "agent");
;             asm volatile("s_waitcnt vmcnt(0)" ::: "memory");
;             const unsigned og = xb_add(&bar[XB_TOP], 1u);
;             const unsigned tg = og / nx;
;             if (og + 1u == (tg + 1u) * nx) xb_add(&bar[XB_TOPGEN], 1u);
;             else XB_SPIN(xb_ld(&bar[XB_TOPGEN]) == tg, bar);
;             __builtin_amdgcn_fence(__ATOMIC_ACQUIRE, "agent");
;             xb_add(&bar[XB_XGEN(b.x)], 1u);
;             asm volatile("s_waitcnt vmcnt(0)" ::: "memory");
;         } else {
;             XB_SPIN(xb_ld(&bar[XB_XGEN(b.x)]) == gen, bar);
.LBB0_1055:
	v_readlane_b32 s8, v251, 9
	v_readlane_b32 s9, v251, 10
	v_cvt_f32_u32_e32 v1, v4
	v_sub_u32_e32 v6, 0, v4
	v_rcp_iflag_f32_e32 v1, v1
	s_nop 1
	global_atomic_add v5, v3, v211, s[8:9] sc0
	v_mul_f32_e32 v1, 0x4f7ffffe, v1
	v_cvt_u32_f32_e32 v1, v1
	v_mul_lo_u32 v6, v6, v1
	v_mul_hi_u32 v6, v1, v6
	v_add_u32_e32 v1, v1, v6
	s_waitcnt vmcnt(0)
	v_mul_hi_u32 v1, v5, v1
	v_mul_lo_u32 v6, v1, v4
	v_sub_u32_e32 v6, v5, v6
	v_add_u32_e32 v7, 1, v1
	v_cmp_ge_u32_e32 vcc, v6, v4
	v_add_u32_e32 v5, 1, v5
	s_nop 0
	v_cndmask_b32_e32 v1, v1, v7, vcc
	v_sub_u32_e32 v7, v6, v4
	v_cndmask_b32_e32 v6, v6, v7, vcc
	v_add_u32_e32 v7, 1, v1
	v_cmp_ge_u32_e32 vcc, v6, v4
	s_nop 1
	v_cndmask_b32_e32 v1, v1, v7, vcc
	v_mul_lo_u32 v6, v4, v1
	v_add_u32_e32 v4, v6, v4
	v_cmp_ne_u32_e32 vcc, v5, v4
	s_and_saveexec_b64 s[8:9], vcc
	s_xor_b64 s[8:9], exec, s[8:9]
	s_cbranch_execz .LBB0_1069
	v_readlane_b32 s10, v251, 11
	v_readlane_b32 s11, v251, 12
	s_waitcnt lgkmcnt(0)
	s_nop 3
	buffer_inv sc1
	global_load_dword v2, v3, s[10:11] sc1
	s_waitcnt vmcnt(0)
	v_cmp_eq_u32_e32 vcc, v2, v1
	s_and_saveexec_b64 s[10:11], vcc
	s_cbranch_execz .LBB0_1068
	s_mov_b32 s2, 1
	s_mov_b64 s[12:13], 0
	s_branch .LBB0_1059

; __device__ __forceinline__ unsigned xb_ld(unsigned* p)              { return __hip_atomic_load(p, __ATOMIC_RELAXED, __HIP_MEMORY_SCOPE_AGENT); }
; __device__ __forceinline__ unsigned xb_add(unsigned* p, unsigned v) { return __hip_atomic_fetch_add(p, v, __ATOMIC_RELAXED, __HIP_MEMORY_SCOPE_AGENT); }
; #define XB_SPIN(cond, bar) do { unsigned _sp = 0; while (cond) { __builtin_amdgcn_s_sleep(1); \
;     if ((++_sp & 255u) == 0u) { if (xb_ld(&(bar)[XB_TMO])) break; if (_sp > XB_SPIN_CAP) { atomicAdd(&(bar)[XB_TMO], 1u); break; } } } } while (0)
; __device__ __forceinline__ void xcd_barrier(const XcdBarrier& b) {
;     ...
;         if (old + 1u == (gen + 1u) * nloc) {
;             __builtin_amdgcn_fence(__ATOMIC_RELEASE, "agent");
;             asm volatile("s_waitcnt vmcnt(0)" ::: "memory");
;             const unsigned og = xb_add(&bar[XB_TOP], 1u);
;             const unsigned tg = og / nx;
;             if (og + 1u == (tg + 1u) * nx) xb_add(&bar[XB_TOPGEN], 1u);
;             else XB_SPIN(xb_ld(&bar[XB_TOPGEN]) == tg, bar);
;             __builtin_amdgcn_fence(__ATOMIC_ACQUIRE, "agent");
;             xb_add(&bar[XB_XGEN(b.x)], 1u);
;             asm volatile("s_waitcnt vmcnt(0)" ::: "memory");
;         } else {
;             XB_SPIN(xb_ld(&bar[XB_XGEN(b.x)]) == gen, bar);
;             __builtin_amdgcn_fence(__ATOMIC_ACQUIRE, "agent");
.LBB0_1068:
	s_or_b64 exec, exec, s[10:11]
	s_waitcnt vmcnt(0)
	s_waitcnt vmcnt(0)
.LBB0_1069:
	s_andn2_saveexec_b64 s[8:9], s[8:9]
	s_cbranch_execz .LBB0_1087
	s_mov_b64 s[8:9], exec
	buffer_inv sc1
	buffer_wbl2 sc1
	s_waitcnt lgkmcnt(0)
	s_waitcnt vmcnt(0)
	v_mbcnt_lo_u32_b32 v1, s8, 0
	v_mbcnt_hi_u32_b32 v1, s9, v1
	v_cmp_eq_u32_e32 vcc, 0, v1
	s_and_saveexec_b64 s[10:11], vcc
	s_cbranch_execz .LBB0_1072
	s_bcnt1_i32_b64 s2, s[8:9]
	v_readlane_b32 s8, v251, 13
	v_mov_b32_e32 v4, s2
	v_readlane_b32 s9, v251, 14
	s_nop 4
	global_atomic_add v4, v3, v4, s[8:9] sc0

; __device__ __forceinline__ unsigned xb_add(unsigned* p, unsigned v) { return __hip_atomic_fetch_add(p, v, __ATOMIC_RELAXED, __HIP_MEMORY_SCOPE_AGENT); }
; __device__ __forceinline__ void xcd_barrier(const XcdBarrier& b) {
;     ...
;             __builtin_amdgcn_fence(__ATOMIC_ACQUIRE, "agent");
;             xb_add(&bar[XB_XGEN(b.x)], 1u);
;             asm volatile("s_waitcnt vmcnt(0)" ::: "memory");
.LBB0_1086:
	s_or_b64 exec, exec, s[8:9]
	v_readlane_b32 s8, v251, 11
	v_readlane_b32 s9, v251, 12
	s_waitcnt vmcnt(0)
	s_nop 0
	s_nop 2
	global_atomic_add v3, v211, s[8:9]
	s_waitcnt vmcnt(0)

; __device__ __forceinline__ unsigned xb_ld(unsigned* p)              { return __hip_atomic_load(p, __ATOMIC_RELAXED, __HIP_MEMORY_SCOPE_AGENT); }
; __device__ __forceinline__ unsigned xb_add(unsigned* p, unsigned v) { return __hip_atomic_fetch_add(p, v, __ATOMIC_RELAXED, __HIP_MEMORY_SCOPE_AGENT); }
; #define XB_SPIN(cond, bar) do { unsigned _sp = 0; while (cond) { __builtin_amdgcn_s_sleep(1); \
;     if ((++_sp & 255u) == 0u) { if (xb_ld(&(bar)[XB_TMO])) break; if (_sp > XB_SPIN_CAP) { atomicAdd(&(bar)[XB_TMO], 1u); break; } } } } while (0)
; __device__ __forceinline__ void xcd_barrier(const XcdBarrier& b) {
;     ...
;         const unsigned old = xb_add(&bar[XB_XSUB(b.x)], 1u);
;         const unsigned gen = old / nloc;
;         if (old + 1u == (gen + 1u) * nloc) {
;             __builtin_amdgcn_fence(__ATOMIC_RELEASE, "agent");
;             asm volatile("s_waitcnt vmcnt(0)" ::: "memory");
;             const unsigned og = xb_add(&bar[XB_TOP], 1u);
;             const unsigned tg = og / nx;
;             if (og + 1u == (tg + 1u) * nx) xb_add(&bar[XB_TOPGEN], 1u);
;             else XB_SPIN(xb_ld(&bar[XB_TOPGEN]) == tg, bar);
;             __builtin_amdgcn_fence(__ATOMIC_ACQUIRE, "agent");
;             xb_add(&bar[XB_XGEN(b.x)], 1u);
;             asm volatile("s_waitcnt vmcnt(0)" ::: "memory");
;         } else {
;             XB_SPIN(xb_ld(&bar[XB_XGEN(b.x)]) == gen, bar);
.LBB0_1664:
	v_readlane_b32 s6, v251, 9
	v_readlane_b32 s7, v251, 10
	v_cvt_f32_u32_e32 v1, v4
	v_sub_u32_e32 v6, 0, v4
	v_rcp_iflag_f32_e32 v1, v1
	s_nop 1
	global_atomic_add v5, v3, v211, s[6:7] sc0
	v_mul_f32_e32 v1, 0x4f7ffffe, v1
	v_cvt_u32_f32_e32 v1, v1
	v_mul_lo_u32 v6, v6, v1
	v_mul_hi_u32 v6, v1, v6
	v_add_u32_e32 v1, v1, v6
	s_waitcnt vmcnt(0)
	v_mul_hi_u32 v1, v5, v1
	v_mul_lo_u32 v6, v1, v4
	v_sub_u32_e32 v6, v5, v6
	v_add_u32_e32 v7, 1, v1
	v_cmp_ge_u32_e32 vcc, v6, v4
	v_add_u32_e32 v5, 1, v5
	s_nop 0
	v_cndmask_b32_e32 v1, v1, v7, vcc
	v_sub_u32_e32 v7, v6, v4
	v_cndmask_b32_e32 v6, v6, v7, vcc
	v_add_u32_e32 v7, 1, v1
	v_cmp_ge_u32_e32 vcc, v6, v4
	s_nop 1
	v_cndmask_b32_e32 v1, v1, v7, vcc
	v_mul_lo_u32 v6, v4, v1
	v_add_u32_e32 v4, v6, v4
	v_cmp_ne_u32_e32 vcc, v5, v4
	s_and_saveexec_b64 s[6:7], vcc
	s_xor_b64 s[6:7], exec, s[6:7]
	s_cbranch_execz .LBB0_1678
	v_readlane_b32 s8, v251, 11
	v_readlane_b32 s9, v251, 12
	s_waitcnt lgkmcnt(0)
	s_nop 3
	buffer_inv sc1
	global_load_dword v2, v3, s[8:9] sc1
	s_waitcnt vmcnt(0)
	v_cmp_eq_u32_e32 vcc, v2, v1
	s_and_saveexec_b64 s[8:9], vcc
	s_cbranch_execz .LBB0_1677
	s_mov_b32 s2, 1
	s_mov_b64 s[10:11], 0
	s_branch .LBB0_1668

; __device__ __forceinline__ unsigned xb_add(unsigned* p, unsigned v) { return __hip_atomic_fetch_add(p, v, __ATOMIC_RELAXED, __HIP_MEMORY_SCOPE_AGENT); }
; __device__ __forceinline__ void xcd_barrier(const XcdBarrier& b) {
;     ...
;         if (old + 1u == (gen + 1u) * nloc) {
;             __builtin_amdgcn_fence(__ATOMIC_RELEASE, "agent");
;             asm volatile("s_waitcnt vmcnt(0)" ::: "memory");
;             const unsigned og = xb_add(&bar[XB_TOP], 1u);
;             const unsigned tg = og / nx;
;             if (og + 1u == (tg + 1u) * nx) xb_add(&bar[XB_TOPGEN], 1u);
.LBB0_1678:
	s_andn2_saveexec_b64 s[6:7], s[6:7]
	s_cbranch_execz .LBB0_1696
	s_mov_b64 s[6:7], exec
	buffer_inv sc1
	buffer_wbl2 sc1
	s_waitcnt lgkmcnt(0)
	s_waitcnt vmcnt(0)
	v_mbcnt_lo_u32_b32 v1, s6, 0
	v_mbcnt_hi_u32_b32 v1, s7, v1
	v_cmp_eq_u32_e32 vcc, 0, v1
	s_and_saveexec_b64 s[8:9], vcc
	s_cbranch_execz .LBB0_1681
	s_bcnt1_i32_b64 s2, s[6:7]
	v_readlane_b32 s6, v251, 13
	v_mov_b32_e32 v4, s2
	v_readlane_b32 s7, v251, 14
	s_nop 4
	global_atomic_add v4, v3, v4, s[6:7] sc0
